# v29 + prologue weight transposes with 32 loads in flight per wave, code padded so later hot loops keep their placement
# speedup vs baseline: 1.0082x; 1.0082x over previous
; __device__ __forceinline__ int launder_s(int v) { asm volatile("" : "+s"(v)); return v; }
; __global__ void __launch_bounds__(512) fwd_megakernel(Args a) {
;     ...
;     if (a.ph_lo == 0) {
;         { const int bx0 = launder_s(blockIdx.x); if (bx0 == 0) { int t0_ = threadIdx.x; asm volatile("" : "+v"(t0_)); for (int i = t0_; i < XCD_BAR_WORDS; i += 512) __hip_atomic_store((unsigned*)a.ws + i, 0u, __ATOMIC_RELAXED, __HIP_MEMORY_SCOPE_AGENT); } }
;         phase_prologue(a, lds);
;         if (a.ph_hi > 1) { grid.sync(); xbar = xcd_barrier_post((unsigned*)a.ws, bst); }
;     }
;     for (int ph = (a.ph_lo > 1 ? a.ph_lo : 1); ph < a.ph_hi; ++ph) {
;         asm volatile("" : "+s"(ws));
;         const float* mod = (const float*)(ws + WS_MOD);
;         const float* normg = a.in[I_NORMG];
;         bf16_t* Xbf = (bf16_t*)(ws + WS_Y);
;         bf16_t* Abuf = (bf16_t*)(ws + WS_A); bf16_t* Ybuf = Abuf; bf16_t* Big = (bf16_t*)(ws + WS_BIG);
;         bf16_t* Obuf = (bf16_t*)(ws + WS_BIG + (size_t)MALL * QKVW * 2);
;         const int G = launder_s(gridDim.x), bxl = launder_s(blockIdx.x);
.LBB0_85:
	s_nop 0
	s_mov_b64 s[68:69], s[80:81]
	v_writelane_b32 v254, s68, 24
	s_nop 1
	v_writelane_b32 v254, s69, 25
	v_writelane_b32 v254, s70, 26
	v_writelane_b32 v254, s71, 27
	v_writelane_b32 v254, s72, 28
	v_writelane_b32 v254, s73, 29
	v_writelane_b32 v254, s74, 30
	v_writelane_b32 v254, s75, 31
	s_nop 0
	v_readlane_b32 s8, v254, 16
	v_readlane_b32 s12, v254, 20
	v_readlane_b32 s13, v254, 21
	s_max_i32 s23, s12, 1
	v_readlane_b32 s10, v254, 18
	v_readlane_b32 s11, v254, 19
	v_readlane_b32 s14, v254, 22
	v_readlane_b32 s15, v254, 23
	s_cmp_ge_i32 s23, s13
	v_readlane_b32 s9, v254, 17
	s_cbranch_scc0 .LBB0_86
	s_getpc_b64 s[98:99]
